# weight-prep phase: the per-row gain loads of the two gain-scaled weight transposes (W_uq, W_ukv) are all in flight at once instead of one round trip per element pair; otherwise as v84
# speedup vs baseline: 1.0112x; 1.0049x over previous
; __device__ __forceinline__ void transpose_item(const float* __restrict__ W, int K, int N, bf16_t* WT, int KD, int item, int mat, const float* __restrict__ ks, float* scr, int lane) {
;     const int nkb = KD / 64, pb = item / nkb, kb = item - pb * nkb, p0 = pb * 32, k0 = kb * 64;
;     const int src = srcmap(mat, p0 + (lane & 31));
;     float tv[32];
; #pragma unroll
;     for (int i = 0; i < 32; ++i) {
;         const int k = k0 + 2 * i + (lane >> 5);
;         float v = 0.f;
;         if (src >= 0 && k < K) { v = W[(size_t)k * N + src]; if (ks) v *= ks[k]; }
;         tv[i] = v;
;     }
.LBB0_1886:
	s_andn2_b64 vcc, exec, s[0:1]
	s_cbranch_vccnz .LBB0_1984
	s_load_dwordx2 s[0:1], s[6:7], 0x68
	s_load_dwordx2 s[34:35], s[6:7], 0x58
	v_mov_b32_e32 v21, v36
	v_mov_b32_e32 v17, 0
	v_mov_b32_e32 v32, 0
	s_waitcnt lgkmcnt(0)
	s_add_u32 s0, s0, s14
	s_addc_u32 s1, s1, s15
	s_add_i32 s19, s27, 0xfffff420
	s_add_u32 s24, s34, s16
	s_addc_u32 s25, s35, s17
	s_lshr_b32 s30, s19, 2
	s_lshl_b32 s18, s30, 5
	s_lshl_b32 s30, s30, 8
	s_lshl_b32 s19, s19, 6
	s_sub_i32 s30, s19, s30
	v_or_b32_e32 v20, s18, v1
	v_or_b32_e32 v18, s30, v3
	v_lshl_add_u64 v[20:21], v[20:21], 2, s[0:1]
	s_cmp_lg_u64 s[34:35], 0
	s_movk_i32 s0, 0x80
	v_cmp_gt_i32_e32 vcc, s0, v18
	s_cselect_b64 s[0:1], -1, 0
	v_cndmask_b32_e64 v19, 0, 1, s[0:1]
	v_cmp_ne_u32_e64 s[38:39], 1, v19
	v_mov_b32_e32 v136, 1.0
	v_mov_b32_e32 v137, 1.0
	v_mov_b32_e32 v138, 1.0
	v_mov_b32_e32 v139, 1.0
	v_mov_b32_e32 v140, 1.0
	v_mov_b32_e32 v141, 1.0
	v_mov_b32_e32 v142, 1.0
	v_mov_b32_e32 v143, 1.0
	v_mov_b32_e32 v144, 1.0
	v_mov_b32_e32 v145, 1.0
	v_mov_b32_e32 v146, 1.0
	v_mov_b32_e32 v147, 1.0
	v_mov_b32_e32 v148, 1.0
	v_mov_b32_e32 v149, 1.0
	v_mov_b32_e32 v150, 1.0
	v_mov_b32_e32 v151, 1.0
	v_mov_b32_e32 v152, 1.0
	v_mov_b32_e32 v153, 1.0
	v_mov_b32_e32 v154, 1.0
	v_mov_b32_e32 v155, 1.0
	v_mov_b32_e32 v156, 1.0
	v_mov_b32_e32 v157, 1.0
	v_mov_b32_e32 v158, 1.0
	v_mov_b32_e32 v159, 1.0
	v_mov_b32_e32 v174, 1.0
	v_mov_b32_e32 v175, 1.0
	v_mov_b32_e32 v176, 1.0
	v_mov_b32_e32 v177, 1.0
	v_mov_b32_e32 v178, 1.0
	v_mov_b32_e32 v179, 1.0
	v_mov_b32_e32 v180, 1.0
	v_mov_b32_e32 v181, 1.0
	s_and_saveexec_b64 s[0:1], vcc
	s_cbranch_execz .LBB0_1890
	v_ashrrev_i32_e32 v19, 31, v18
	v_lshlrev_b64 v[22:23], 12, v[18:19]
	v_lshl_add_u64 v[22:23], v[20:21], 0, v[22:23]
	global_load_dword v32, v[22:23], off
	s_and_b64 vcc, exec, s[38:39]
	s_cbranch_vccnz .LBB0_1890
	v_lshl_add_u64 v[22:23], v[18:19], 2, s[24:25]
	global_load_dword v136, v[22:23], off
.LBB0_1890:
	s_or_b64 exec, exec, s[0:1]
	v_or_b32_e32 v22, 2, v18
	s_movk_i32 s0, 0x80
	v_cmp_gt_i32_e32 vcc, s0, v22
	s_and_saveexec_b64 s[0:1], vcc
	s_cbranch_execz .LBB0_1893
	v_ashrrev_i32_e32 v23, 31, v22
	v_lshlrev_b64 v[22:23], 12, v[22:23]
	v_lshl_add_u64 v[22:23], v[20:21], 0, v[22:23]
	global_load_dword v17, v[22:23], off
	s_and_b64 vcc, exec, s[38:39]
	s_cbranch_vccnz .LBB0_1893
	v_ashrrev_i32_e32 v19, 31, v18
	v_lshl_add_u64 v[22:23], v[18:19], 2, s[24:25]
	global_load_dword v137, v[22:23], off offset:8
.LBB0_1893:
	s_or_b64 exec, exec, s[0:1]
	v_or_b32_e32 v22, 4, v18
	s_movk_i32 s0, 0x80
	v_cmp_gt_i32_e32 vcc, s0, v22
	v_mov_b32_e32 v33, 0
	v_mov_b32_e32 v34, 0
	s_and_saveexec_b64 s[0:1], vcc
	s_cbranch_execz .LBB0_1896
	v_ashrrev_i32_e32 v23, 31, v22
	v_lshlrev_b64 v[22:23], 12, v[22:23]
	v_lshl_add_u64 v[22:23], v[20:21], 0, v[22:23]
	global_load_dword v34, v[22:23], off
	s_and_b64 vcc, exec, s[38:39]
	s_cbranch_vccnz .LBB0_1896
	v_ashrrev_i32_e32 v19, 31, v18
	v_lshl_add_u64 v[22:23], v[18:19], 2, s[24:25]
	global_load_dword v138, v[22:23], off offset:16
.LBB0_1896:
	s_or_b64 exec, exec, s[0:1]
	v_or_b32_e32 v22, 6, v18
	s_movk_i32 s0, 0x80
	v_cmp_gt_i32_e32 vcc, s0, v22
	s_and_saveexec_b64 s[0:1], vcc
	s_cbranch_execz .LBB0_1899
	v_ashrrev_i32_e32 v23, 31, v22
	v_lshlrev_b64 v[22:23], 12, v[22:23]
	v_lshl_add_u64 v[22:23], v[20:21], 0, v[22:23]
	global_load_dword v33, v[22:23], off
	s_and_b64 vcc, exec, s[38:39]
	s_cbranch_vccnz .LBB0_1899
	v_ashrrev_i32_e32 v19, 31, v18
	v_lshl_add_u64 v[22:23], v[18:19], 2, s[24:25]
	global_load_dword v139, v[22:23], off offset:24
.LBB0_1899:
	s_or_b64 exec, exec, s[0:1]
	v_or_b32_e32 v22, 8, v18
	s_movk_i32 s0, 0x80
	v_cmp_gt_i32_e32 vcc, s0, v22
	v_mov_b32_e32 v35, 0
	v_mov_b32_e32 v37, 0
	s_and_saveexec_b64 s[0:1], vcc
	s_cbranch_execz .LBB0_1902
	v_ashrrev_i32_e32 v23, 31, v22
	v_lshlrev_b64 v[22:23], 12, v[22:23]
	v_lshl_add_u64 v[22:23], v[20:21], 0, v[22:23]
	global_load_dword v37, v[22:23], off
	s_and_b64 vcc, exec, s[38:39]
	s_cbranch_vccnz .LBB0_1902
	v_ashrrev_i32_e32 v19, 31, v18
	v_lshl_add_u64 v[22:23], v[18:19], 2, s[24:25]
	global_load_dword v140, v[22:23], off offset:32
.LBB0_1902:
	s_or_b64 exec, exec, s[0:1]
	v_or_b32_e32 v22, 10, v18
	s_movk_i32 s0, 0x80
	v_cmp_gt_i32_e32 vcc, s0, v22
	s_and_saveexec_b64 s[0:1], vcc
	s_cbranch_execz .LBB0_1905
	v_ashrrev_i32_e32 v23, 31, v22
	v_lshlrev_b64 v[22:23], 12, v[22:23]
	v_lshl_add_u64 v[22:23], v[20:21], 0, v[22:23]
	global_load_dword v35, v[22:23], off
	s_and_b64 vcc, exec, s[38:39]
	s_cbranch_vccnz .LBB0_1905
	v_ashrrev_i32_e32 v19, 31, v18
	v_lshl_add_u64 v[22:23], v[18:19], 2, s[24:25]
	global_load_dword v141, v[22:23], off offset:40
.LBB0_1905:
	s_or_b64 exec, exec, s[0:1]
	v_or_b32_e32 v22, 12, v18
	s_movk_i32 s0, 0x80
	v_cmp_gt_i32_e32 vcc, s0, v22
	v_mov_b32_e32 v38, 0
	v_mov_b32_e32 v39, 0
	s_and_saveexec_b64 s[0:1], vcc
	s_cbranch_execz .LBB0_1908
	v_ashrrev_i32_e32 v23, 31, v22
	v_lshlrev_b64 v[22:23], 12, v[22:23]
	v_lshl_add_u64 v[22:23], v[20:21], 0, v[22:23]
	global_load_dword v39, v[22:23], off
	s_and_b64 vcc, exec, s[38:39]
	s_cbranch_vccnz .LBB0_1908
	v_ashrrev_i32_e32 v19, 31, v18
	v_lshl_add_u64 v[22:23], v[18:19], 2, s[24:25]
	global_load_dword v142, v[22:23], off offset:48
.LBB0_1908:
	s_or_b64 exec, exec, s[0:1]
	v_or_b32_e32 v22, 14, v18
	s_movk_i32 s0, 0x80
	v_cmp_gt_i32_e32 vcc, s0, v22
	s_and_saveexec_b64 s[0:1], vcc
	s_cbranch_execz .LBB0_1911
	v_ashrrev_i32_e32 v23, 31, v22
	v_lshlrev_b64 v[22:23], 12, v[22:23]
	v_lshl_add_u64 v[22:23], v[20:21], 0, v[22:23]
	global_load_dword v38, v[22:23], off
	s_and_b64 vcc, exec, s[38:39]
	s_cbranch_vccnz .LBB0_1911
	v_ashrrev_i32_e32 v19, 31, v18
	v_lshl_add_u64 v[22:23], v[18:19], 2, s[24:25]
	global_load_dword v143, v[22:23], off offset:56
; __device__ __forceinline__ void transpose_item(const float* __restrict__ W, int K, int N, bf16_t* WT, int KD, int item, int mat, const float* __restrict__ ks, float* scr, int lane) {
;     ...
;     for (int i = 0; i < 32; ++i) {
;         const int k = k0 + 2 * i + (lane >> 5);
;         float v = 0.f;
;         if (src >= 0 && k < K) { v = W[(size_t)k * N + src]; if (ks) v *= ks[k]; }
;         tv[i] = v;
;     }
.LBB0_1911:
	s_or_b64 exec, exec, s[0:1]
	v_or_b32_e32 v22, 16, v18
	s_movk_i32 s0, 0x80
	v_cmp_gt_i32_e32 vcc, s0, v22
	v_mov_b32_e32 v41, 0
	v_mov_b32_e32 v42, 0
	s_and_saveexec_b64 s[0:1], vcc
	s_cbranch_execz .LBB0_1914
	v_ashrrev_i32_e32 v23, 31, v22
	v_lshlrev_b64 v[22:23], 12, v[22:23]
	v_lshl_add_u64 v[22:23], v[20:21], 0, v[22:23]
	global_load_dword v42, v[22:23], off
	s_and_b64 vcc, exec, s[38:39]
	s_cbranch_vccnz .LBB0_1914
	v_ashrrev_i32_e32 v19, 31, v18
	v_lshl_add_u64 v[22:23], v[18:19], 2, s[24:25]
	global_load_dword v144, v[22:23], off offset:64
.LBB0_1914:
	s_or_b64 exec, exec, s[0:1]
	v_or_b32_e32 v22, 18, v18
	s_movk_i32 s0, 0x80
	v_cmp_gt_i32_e32 vcc, s0, v22
	s_and_saveexec_b64 s[0:1], vcc
	s_cbranch_execz .LBB0_1917
	v_ashrrev_i32_e32 v23, 31, v22
	v_lshlrev_b64 v[22:23], 12, v[22:23]
	v_lshl_add_u64 v[22:23], v[20:21], 0, v[22:23]
	global_load_dword v41, v[22:23], off
	s_and_b64 vcc, exec, s[38:39]
	s_cbranch_vccnz .LBB0_1917
	v_ashrrev_i32_e32 v19, 31, v18
	v_lshl_add_u64 v[22:23], v[18:19], 2, s[24:25]
	global_load_dword v145, v[22:23], off offset:72
.LBB0_1917:
	s_or_b64 exec, exec, s[0:1]
	v_or_b32_e32 v22, 20, v18
	s_movk_i32 s0, 0x80
	v_cmp_gt_i32_e32 vcc, s0, v22
	v_mov_b32_e32 v43, 0
	v_mov_b32_e32 v48, 0
	s_and_saveexec_b64 s[0:1], vcc
	s_cbranch_execz .LBB0_1920
	v_ashrrev_i32_e32 v23, 31, v22
	v_lshlrev_b64 v[22:23], 12, v[22:23]
	v_lshl_add_u64 v[22:23], v[20:21], 0, v[22:23]
	global_load_dword v48, v[22:23], off
	s_and_b64 vcc, exec, s[38:39]
	s_cbranch_vccnz .LBB0_1920
	v_ashrrev_i32_e32 v19, 31, v18
	v_lshl_add_u64 v[22:23], v[18:19], 2, s[24:25]
	global_load_dword v146, v[22:23], off offset:80
.LBB0_1920:
	s_or_b64 exec, exec, s[0:1]
	v_or_b32_e32 v22, 22, v18
	s_movk_i32 s0, 0x80
	v_cmp_gt_i32_e32 vcc, s0, v22
	s_and_saveexec_b64 s[0:1], vcc
	s_cbranch_execz .LBB0_1923
	v_ashrrev_i32_e32 v23, 31, v22
	v_lshlrev_b64 v[22:23], 12, v[22:23]
	v_lshl_add_u64 v[22:23], v[20:21], 0, v[22:23]
	global_load_dword v43, v[22:23], off
	s_and_b64 vcc, exec, s[38:39]
	s_cbranch_vccnz .LBB0_1923
	v_ashrrev_i32_e32 v19, 31, v18
	v_lshl_add_u64 v[22:23], v[18:19], 2, s[24:25]
	global_load_dword v147, v[22:23], off offset:88
.LBB0_1923:
	s_or_b64 exec, exec, s[0:1]
	v_or_b32_e32 v22, 24, v18
	s_movk_i32 s0, 0x80
	v_cmp_gt_i32_e32 vcc, s0, v22
	v_mov_b32_e32 v49, 0
	v_mov_b32_e32 v50, 0
	s_and_saveexec_b64 s[0:1], vcc
	s_cbranch_execz .LBB0_1926
	v_ashrrev_i32_e32 v23, 31, v22
	v_lshlrev_b64 v[22:23], 12, v[22:23]
	v_lshl_add_u64 v[22:23], v[20:21], 0, v[22:23]
	global_load_dword v50, v[22:23], off
	s_and_b64 vcc, exec, s[38:39]
	s_cbranch_vccnz .LBB0_1926
	v_ashrrev_i32_e32 v19, 31, v18
	v_lshl_add_u64 v[22:23], v[18:19], 2, s[24:25]
	global_load_dword v148, v[22:23], off offset:96
.LBB0_1926:
	s_or_b64 exec, exec, s[0:1]
	v_or_b32_e32 v22, 26, v18
	s_movk_i32 s0, 0x80
	v_cmp_gt_i32_e32 vcc, s0, v22
	s_and_saveexec_b64 s[0:1], vcc
	s_cbranch_execz .LBB0_1929
	v_ashrrev_i32_e32 v23, 31, v22
	v_lshlrev_b64 v[22:23], 12, v[22:23]
	v_lshl_add_u64 v[22:23], v[20:21], 0, v[22:23]
	global_load_dword v49, v[22:23], off
	s_and_b64 vcc, exec, s[38:39]
	s_cbranch_vccnz .LBB0_1929
	v_ashrrev_i32_e32 v19, 31, v18
	v_lshl_add_u64 v[22:23], v[18:19], 2, s[24:25]
	global_load_dword v149, v[22:23], off offset:104
.LBB0_1929:
	s_or_b64 exec, exec, s[0:1]
	v_or_b32_e32 v22, 28, v18
	s_movk_i32 s0, 0x80
	v_cmp_gt_i32_e32 vcc, s0, v22
	v_mov_b32_e32 v51, 0
	v_mov_b32_e32 v52, 0
	s_and_saveexec_b64 s[0:1], vcc
	s_cbranch_execz .LBB0_1932
	v_ashrrev_i32_e32 v23, 31, v22
	v_lshlrev_b64 v[22:23], 12, v[22:23]
	v_lshl_add_u64 v[22:23], v[20:21], 0, v[22:23]
	global_load_dword v52, v[22:23], off
	s_and_b64 vcc, exec, s[38:39]
	s_cbranch_vccnz .LBB0_1932
	v_ashrrev_i32_e32 v19, 31, v18
	v_lshl_add_u64 v[22:23], v[18:19], 2, s[24:25]
	global_load_dword v150, v[22:23], off offset:112
.LBB0_1932:
	s_or_b64 exec, exec, s[0:1]
	v_or_b32_e32 v22, 30, v18
	s_movk_i32 s0, 0x80
	v_cmp_gt_i32_e32 vcc, s0, v22
	s_and_saveexec_b64 s[0:1], vcc
	s_cbranch_execz .LBB0_1935
	v_ashrrev_i32_e32 v23, 31, v22
	v_lshlrev_b64 v[22:23], 12, v[22:23]
	v_lshl_add_u64 v[22:23], v[20:21], 0, v[22:23]
	global_load_dword v51, v[22:23], off
	s_and_b64 vcc, exec, s[38:39]
	s_cbranch_vccnz .LBB0_1935
	v_ashrrev_i32_e32 v19, 31, v18
	v_lshl_add_u64 v[22:23], v[18:19], 2, s[24:25]
	global_load_dword v151, v[22:23], off offset:120
.LBB0_1935:
	s_or_b64 exec, exec, s[0:1]
	v_or_b32_e32 v22, 32, v18
	s_movk_i32 s0, 0x80
	v_cmp_gt_i32_e32 vcc, s0, v22
	v_mov_b32_e32 v53, 0
	v_mov_b32_e32 v54, 0
	s_and_saveexec_b64 s[0:1], vcc
	s_cbranch_execz .LBB0_1938
	v_ashrrev_i32_e32 v23, 31, v22
	v_lshlrev_b64 v[22:23], 12, v[22:23]
	v_lshl_add_u64 v[22:23], v[20:21], 0, v[22:23]
	global_load_dword v54, v[22:23], off
	s_and_b64 vcc, exec, s[38:39]
	s_cbranch_vccnz .LBB0_1938
	v_ashrrev_i32_e32 v19, 31, v18
	v_lshl_add_u64 v[22:23], v[18:19], 2, s[24:25]
	global_load_dword v152, v[22:23], off offset:128
.LBB0_1938:
	s_or_b64 exec, exec, s[0:1]
	v_or_b32_e32 v22, 34, v18
	s_movk_i32 s0, 0x80
	v_cmp_gt_i32_e32 vcc, s0, v22
	s_and_saveexec_b64 s[0:1], vcc
	s_cbranch_execz .LBB0_1941
	v_ashrrev_i32_e32 v23, 31, v22
	v_lshlrev_b64 v[22:23], 12, v[22:23]
	v_lshl_add_u64 v[22:23], v[20:21], 0, v[22:23]
	global_load_dword v53, v[22:23], off
	s_and_b64 vcc, exec, s[38:39]
	s_cbranch_vccnz .LBB0_1941
	v_ashrrev_i32_e32 v19, 31, v18
	v_lshl_add_u64 v[22:23], v[18:19], 2, s[24:25]
	global_load_dword v153, v[22:23], off offset:136
; __device__ __forceinline__ void transpose_item(const float* __restrict__ W, int K, int N, bf16_t* WT, int KD, int item, int mat, const float* __restrict__ ks, float* scr, int lane) {
;     ...
;     for (int i = 0; i < 32; ++i) {
;         const int k = k0 + 2 * i + (lane >> 5);
;         float v = 0.f;
;         if (src >= 0 && k < K) { v = W[(size_t)k * N + src]; if (ks) v *= ks[k]; }
;         tv[i] = v;
;     }
.LBB0_1941:
	s_or_b64 exec, exec, s[0:1]
	v_or_b32_e32 v22, 36, v18
	s_movk_i32 s0, 0x80
	v_cmp_gt_i32_e32 vcc, s0, v22
	v_mov_b32_e32 v55, 0
	v_mov_b32_e32 v56, 0
	s_and_saveexec_b64 s[0:1], vcc
	s_cbranch_execz .LBB0_1944
	v_ashrrev_i32_e32 v23, 31, v22
	v_lshlrev_b64 v[22:23], 12, v[22:23]
	v_lshl_add_u64 v[22:23], v[20:21], 0, v[22:23]
	global_load_dword v56, v[22:23], off
	s_and_b64 vcc, exec, s[38:39]
	s_cbranch_vccnz .LBB0_1944
	v_ashrrev_i32_e32 v19, 31, v18
	v_lshl_add_u64 v[22:23], v[18:19], 2, s[24:25]
	global_load_dword v154, v[22:23], off offset:144
.LBB0_1944:
	s_or_b64 exec, exec, s[0:1]
	v_or_b32_e32 v22, 38, v18
	s_movk_i32 s0, 0x80
	v_cmp_gt_i32_e32 vcc, s0, v22
	s_and_saveexec_b64 s[0:1], vcc
	s_cbranch_execz .LBB0_1947
	v_ashrrev_i32_e32 v23, 31, v22
	v_lshlrev_b64 v[22:23], 12, v[22:23]
	v_lshl_add_u64 v[22:23], v[20:21], 0, v[22:23]
	global_load_dword v55, v[22:23], off
	s_and_b64 vcc, exec, s[38:39]
	s_cbranch_vccnz .LBB0_1947
	v_ashrrev_i32_e32 v19, 31, v18
	v_lshl_add_u64 v[22:23], v[18:19], 2, s[24:25]
	global_load_dword v155, v[22:23], off offset:152
.LBB0_1947:
	s_or_b64 exec, exec, s[0:1]
	v_or_b32_e32 v22, 40, v18
	s_movk_i32 s0, 0x80
	v_cmp_gt_i32_e32 vcc, s0, v22
	v_mov_b32_e32 v57, 0
	v_mov_b32_e32 v58, 0
	s_and_saveexec_b64 s[0:1], vcc
	s_cbranch_execz .LBB0_1950
	v_ashrrev_i32_e32 v23, 31, v22
	v_lshlrev_b64 v[22:23], 12, v[22:23]
	v_lshl_add_u64 v[22:23], v[20:21], 0, v[22:23]
	global_load_dword v58, v[22:23], off
	s_and_b64 vcc, exec, s[38:39]
	s_cbranch_vccnz .LBB0_1950
	v_ashrrev_i32_e32 v19, 31, v18
	v_lshl_add_u64 v[22:23], v[18:19], 2, s[24:25]
	global_load_dword v156, v[22:23], off offset:160
.LBB0_1950:
	s_or_b64 exec, exec, s[0:1]
	v_or_b32_e32 v22, 42, v18
	s_movk_i32 s0, 0x80
	v_cmp_gt_i32_e32 vcc, s0, v22
	s_and_saveexec_b64 s[0:1], vcc
	s_cbranch_execz .LBB0_1953
	v_ashrrev_i32_e32 v23, 31, v22
	v_lshlrev_b64 v[22:23], 12, v[22:23]
	v_lshl_add_u64 v[22:23], v[20:21], 0, v[22:23]
	global_load_dword v57, v[22:23], off
	s_and_b64 vcc, exec, s[38:39]
	s_cbranch_vccnz .LBB0_1953
	v_ashrrev_i32_e32 v19, 31, v18
	v_lshl_add_u64 v[22:23], v[18:19], 2, s[24:25]
	global_load_dword v157, v[22:23], off offset:168
.LBB0_1953:
	s_or_b64 exec, exec, s[0:1]
	v_or_b32_e32 v22, 44, v18
	s_movk_i32 s0, 0x80
	v_cmp_gt_i32_e32 vcc, s0, v22
	v_mov_b32_e32 v59, 0
	v_mov_b32_e32 v60, 0
	s_and_saveexec_b64 s[0:1], vcc
	s_cbranch_execz .LBB0_1956
	v_ashrrev_i32_e32 v23, 31, v22
	v_lshlrev_b64 v[22:23], 12, v[22:23]
	v_lshl_add_u64 v[22:23], v[20:21], 0, v[22:23]
	global_load_dword v60, v[22:23], off
	s_and_b64 vcc, exec, s[38:39]
	s_cbranch_vccnz .LBB0_1956
	v_ashrrev_i32_e32 v19, 31, v18
	v_lshl_add_u64 v[22:23], v[18:19], 2, s[24:25]
	global_load_dword v158, v[22:23], off offset:176
.LBB0_1956:
	s_or_b64 exec, exec, s[0:1]
	v_or_b32_e32 v22, 46, v18
	s_movk_i32 s0, 0x80
	v_cmp_gt_i32_e32 vcc, s0, v22
	s_and_saveexec_b64 s[0:1], vcc
	s_cbranch_execz .LBB0_1959
	v_ashrrev_i32_e32 v23, 31, v22
	v_lshlrev_b64 v[22:23], 12, v[22:23]
	v_lshl_add_u64 v[22:23], v[20:21], 0, v[22:23]
	global_load_dword v59, v[22:23], off
	s_and_b64 vcc, exec, s[38:39]
	s_cbranch_vccnz .LBB0_1959
	v_ashrrev_i32_e32 v19, 31, v18
	v_lshl_add_u64 v[22:23], v[18:19], 2, s[24:25]
	global_load_dword v159, v[22:23], off offset:184
.LBB0_1959:
	s_or_b64 exec, exec, s[0:1]
	v_or_b32_e32 v22, 48, v18
	s_movk_i32 s0, 0x80
	v_cmp_gt_i32_e32 vcc, s0, v22
	v_mov_b32_e32 v61, 0
	v_mov_b32_e32 v62, 0
	s_and_saveexec_b64 s[0:1], vcc
	s_cbranch_execz .LBB0_1962
	v_ashrrev_i32_e32 v23, 31, v22
	v_lshlrev_b64 v[22:23], 12, v[22:23]
	v_lshl_add_u64 v[22:23], v[20:21], 0, v[22:23]
	global_load_dword v62, v[22:23], off
	s_and_b64 vcc, exec, s[38:39]
	s_cbranch_vccnz .LBB0_1962
	v_ashrrev_i32_e32 v19, 31, v18
	v_lshl_add_u64 v[22:23], v[18:19], 2, s[24:25]
	global_load_dword v174, v[22:23], off offset:192
.LBB0_1962:
	s_or_b64 exec, exec, s[0:1]
	v_or_b32_e32 v22, 50, v18
	s_movk_i32 s0, 0x80
	v_cmp_gt_i32_e32 vcc, s0, v22
	s_and_saveexec_b64 s[0:1], vcc
	s_cbranch_execz .LBB0_1965
	v_ashrrev_i32_e32 v23, 31, v22
	v_lshlrev_b64 v[22:23], 12, v[22:23]
	v_lshl_add_u64 v[22:23], v[20:21], 0, v[22:23]
	global_load_dword v61, v[22:23], off
	s_and_b64 vcc, exec, s[38:39]
	s_cbranch_vccnz .LBB0_1965
	v_ashrrev_i32_e32 v19, 31, v18
	v_lshl_add_u64 v[22:23], v[18:19], 2, s[24:25]
	global_load_dword v175, v[22:23], off offset:200
.LBB0_1965:
	s_or_b64 exec, exec, s[0:1]
	v_or_b32_e32 v22, 52, v18
	s_movk_i32 s0, 0x80
	v_cmp_gt_i32_e32 vcc, s0, v22
	v_mov_b32_e32 v63, 0
	v_mov_b32_e32 v64, 0
	s_and_saveexec_b64 s[0:1], vcc
	s_cbranch_execz .LBB0_1968
	v_ashrrev_i32_e32 v23, 31, v22
	v_lshlrev_b64 v[22:23], 12, v[22:23]
	v_lshl_add_u64 v[22:23], v[20:21], 0, v[22:23]
	global_load_dword v64, v[22:23], off
	s_and_b64 vcc, exec, s[38:39]
	s_cbranch_vccnz .LBB0_1968
	v_ashrrev_i32_e32 v19, 31, v18
	v_lshl_add_u64 v[22:23], v[18:19], 2, s[24:25]
	global_load_dword v176, v[22:23], off offset:208
.LBB0_1968:
	s_or_b64 exec, exec, s[0:1]
	v_or_b32_e32 v22, 54, v18
	s_movk_i32 s0, 0x80
	v_cmp_gt_i32_e32 vcc, s0, v22
	s_and_saveexec_b64 s[0:1], vcc
	s_cbranch_execz .LBB0_1971
	v_ashrrev_i32_e32 v23, 31, v22
	v_lshlrev_b64 v[22:23], 12, v[22:23]
	v_lshl_add_u64 v[22:23], v[20:21], 0, v[22:23]
	global_load_dword v63, v[22:23], off
	s_and_b64 vcc, exec, s[38:39]
	s_cbranch_vccnz .LBB0_1971
	v_ashrrev_i32_e32 v19, 31, v18
	v_lshl_add_u64 v[22:23], v[18:19], 2, s[24:25]
	global_load_dword v177, v[22:23], off offset:216
; __device__ __forceinline__ unsigned pk2(float lo, float hi) { f32x2_t v = {lo, hi}; bf16x2_t b = __builtin_convertvector(v, bf16x2_t); return __builtin_bit_cast(unsigned, b); }
; __device__ __forceinline__ void transpose_item(const float* __restrict__ W, int K, int N, bf16_t* WT, int KD, int item, int mat, const float* __restrict__ ks, float* scr, int lane) {
;     ...
;     for (int i = 0; i < 32; ++i) {
;         const int k = k0 + 2 * i + (lane >> 5);
;         float v = 0.f;
;         if (src >= 0 && k < K) { v = W[(size_t)k * N + src]; if (ks) v *= ks[k]; }
;         tv[i] = v;
;     }
; #pragma unroll
;     for (int i = 0; i < 32; ++i) scr[(2 * i + (lane >> 5)) * 33 + (lane & 31)] = tv[i];
;     __builtin_amdgcn_fence(__ATOMIC_RELEASE, "workgroup"); __builtin_amdgcn_wave_barrier();
;     const int c = lane & 7;
; #pragma unroll
;     for (int j = 0; j < 4; ++j) {
;         const int n = (lane >> 3) + 8 * j; const float* s = scr + (8 * c) * 33 + n;
;         u32x4 o; o.x = pk2(s[0 * 33], s[1 * 33]); o.y = pk2(s[2 * 33], s[3 * 33]); o.z = pk2(s[4 * 33], s[5 * 33]); o.w = pk2(s[6 * 33], s[7 * 33]);
;         *(u32x4*)(WT + (size_t)(p0 + n) * KD + k0 + 8 * c) = o;
;     }
;     __builtin_amdgcn_fence(__ATOMIC_RELEASE, "workgroup"); __builtin_amdgcn_wave_barrier();
.LBB0_1971:
	s_or_b64 exec, exec, s[0:1]
	v_or_b32_e32 v22, 56, v18
	s_movk_i32 s0, 0x80
	v_cmp_gt_i32_e32 vcc, s0, v22
	v_mov_b32_e32 v65, 0
	v_mov_b32_e32 v66, 0
	s_and_saveexec_b64 s[0:1], vcc
	s_cbranch_execz .LBB0_1974
	v_ashrrev_i32_e32 v23, 31, v22
	v_lshlrev_b64 v[22:23], 12, v[22:23]
	v_lshl_add_u64 v[22:23], v[20:21], 0, v[22:23]
	global_load_dword v66, v[22:23], off
	s_and_b64 vcc, exec, s[38:39]
	s_cbranch_vccnz .LBB0_1974
	v_ashrrev_i32_e32 v19, 31, v18
	v_lshl_add_u64 v[22:23], v[18:19], 2, s[24:25]
	global_load_dword v178, v[22:23], off offset:224
.LBB0_1974:
	s_or_b64 exec, exec, s[0:1]
	v_or_b32_e32 v22, 58, v18
	s_movk_i32 s0, 0x80
	v_cmp_gt_i32_e32 vcc, s0, v22
	s_and_saveexec_b64 s[0:1], vcc
	s_cbranch_execz .LBB0_1977
	v_ashrrev_i32_e32 v23, 31, v22
	v_lshlrev_b64 v[22:23], 12, v[22:23]
	v_lshl_add_u64 v[22:23], v[20:21], 0, v[22:23]
	global_load_dword v65, v[22:23], off
	s_and_b64 vcc, exec, s[38:39]
	s_cbranch_vccnz .LBB0_1977
	v_ashrrev_i32_e32 v19, 31, v18
	v_lshl_add_u64 v[22:23], v[18:19], 2, s[24:25]
	global_load_dword v179, v[22:23], off offset:232
.LBB0_1977:
	s_or_b64 exec, exec, s[0:1]
	v_or_b32_e32 v22, 60, v18
	s_movk_i32 s0, 0x80
	v_cmp_gt_i32_e32 vcc, s0, v22
	v_mov_b32_e32 v67, 0
	s_waitcnt vmcnt(0)
	v_mov_b32_e32 v68, 0
	s_and_saveexec_b64 s[0:1], vcc
	s_cbranch_execz .LBB0_1980
	v_ashrrev_i32_e32 v23, 31, v22
	v_lshlrev_b64 v[22:23], 12, v[22:23]
	v_lshl_add_u64 v[22:23], v[20:21], 0, v[22:23]
	global_load_dword v68, v[22:23], off
	s_and_b64 vcc, exec, s[38:39]
	s_cbranch_vccnz .LBB0_1980
	v_ashrrev_i32_e32 v19, 31, v18
	v_lshl_add_u64 v[22:23], v[18:19], 2, s[24:25]
	global_load_dword v180, v[22:23], off offset:240
.LBB0_1980:
	s_or_b64 exec, exec, s[0:1]
	v_or_b32_e32 v22, 62, v18
	s_movk_i32 s0, 0x80
	v_cmp_gt_i32_e32 vcc, s0, v22
	s_and_saveexec_b64 s[0:1], vcc
	s_cbranch_execz .LBB0_1983
	v_ashrrev_i32_e32 v23, 31, v22
	v_lshlrev_b64 v[22:23], 12, v[22:23]
	v_lshl_add_u64 v[20:21], v[20:21], 0, v[22:23]
	global_load_dword v67, v[20:21], off
	s_and_b64 vcc, exec, s[38:39]
	s_cbranch_vccnz .LBB0_1983
	v_ashrrev_i32_e32 v19, 31, v18
	v_lshl_add_u64 v[18:19], v[18:19], 2, s[24:25]
	global_load_dword v181, v[18:19], off offset:248
.LBB0_1983:
	s_or_b64 exec, exec, s[0:1]
	s_waitcnt vmcnt(0)
	v_mul_f32_e32 v32, v32, v136
	v_mul_f32_e32 v17, v17, v137
	v_mul_f32_e32 v34, v34, v138
	v_mul_f32_e32 v33, v33, v139
	v_mul_f32_e32 v37, v37, v140
	v_mul_f32_e32 v35, v35, v141
	v_mul_f32_e32 v39, v39, v142
	v_mul_f32_e32 v38, v38, v143
	v_mul_f32_e32 v42, v42, v144
	v_mul_f32_e32 v41, v41, v145
	v_mul_f32_e32 v48, v48, v146
	v_mul_f32_e32 v43, v43, v147
	v_mul_f32_e32 v50, v50, v148
	v_mul_f32_e32 v49, v49, v149
	v_mul_f32_e32 v52, v52, v150
	v_mul_f32_e32 v51, v51, v151
	v_mul_f32_e32 v54, v54, v152
	v_mul_f32_e32 v53, v53, v153
	v_mul_f32_e32 v56, v56, v154
	v_mul_f32_e32 v55, v55, v155
	v_mul_f32_e32 v58, v58, v156
	v_mul_f32_e32 v57, v57, v157
	v_mul_f32_e32 v60, v60, v158
	v_mul_f32_e32 v59, v59, v159
	v_mul_f32_e32 v62, v62, v174
	v_mul_f32_e32 v61, v61, v175
	v_mul_f32_e32 v64, v64, v176
	v_mul_f32_e32 v63, v63, v177
	v_mul_f32_e32 v66, v66, v178
	v_mul_f32_e32 v65, v65, v179
	v_mul_f32_e32 v68, v68, v180
	v_mul_f32_e32 v67, v67, v181
	ds_write2_b32 v24, v32, v17 offset1:66
	ds_write2_b32 v24, v34, v33 offset0:132 offset1:198
	v_add_u32_e32 v17, 0x400, v24
	ds_write2_b32 v17, v37, v35 offset0:8 offset1:74
	ds_write2_b32 v17, v39, v38 offset0:140 offset1:206
	v_add_u32_e32 v17, 0x800, v24
	ds_write2_b32 v17, v42, v41 offset0:16 offset1:82
	ds_write2_b32 v17, v48, v43 offset0:148 offset1:214
	v_add_u32_e32 v17, 0xc00, v24
	ds_write2_b32 v17, v50, v49 offset0:24 offset1:90
	ds_write2_b32 v17, v52, v51 offset0:156 offset1:222
	v_add_u32_e32 v17, 0x1000, v24
	ds_write2_b32 v17, v54, v53 offset0:32 offset1:98
	ds_write2_b32 v17, v56, v55 offset0:164 offset1:230
	v_add_u32_e32 v17, 0x1400, v24
	ds_write2_b32 v17, v58, v57 offset0:40 offset1:106
	ds_write2_b32 v17, v60, v59 offset0:172 offset1:238
	v_add_u32_e32 v17, 0x1800, v24
	ds_write2_b32 v17, v62, v61 offset0:48 offset1:114
	ds_write2_b32 v17, v64, v63 offset0:180 offset1:246
	v_add_u32_e32 v17, 0x1c00, v24
	ds_write2_b32 v17, v66, v65 offset0:56 offset1:122
	s_waitcnt vmcnt(0)
	ds_write2_b32 v17, v68, v67 offset0:188 offset1:254
	s_waitcnt lgkmcnt(0)
	ds_read2_b32 v[22:23], v26 offset0:33 offset1:41
	ds_read2_b32 v[32:33], v26 offset1:8
	ds_read2_b32 v[34:35], v26 offset0:66 offset1:74
	ds_read2_b32 v[38:39], v26 offset0:99 offset1:107
	ds_read2_b32 v[42:43], v26 offset0:132 offset1:140
	ds_read2_b32 v[48:49], v26 offset0:165 offset1:173
	ds_read2_b32 v[50:51], v26 offset0:198 offset1:206
	ds_read2_b32 v[52:53], v26 offset0:231 offset1:239
	s_ashr_i32 s31, s30, 31
	v_or_b32_e32 v17, s18, v25
	v_lshl_add_u64 v[54:55], s[30:31], 1, v[10:11]
	v_lshlrev_b32_e32 v56, 9, v17
	v_mov_b32_e32 v57, v36
	s_waitcnt lgkmcnt(6)
	v_cvt_pk_bf16_f32 v18, v32, v22
	s_waitcnt lgkmcnt(4)
	v_cvt_pk_bf16_f32 v19, v34, v38
	s_waitcnt lgkmcnt(2)
	v_cvt_pk_bf16_f32 v20, v42, v48
	s_waitcnt lgkmcnt(0)
	v_cvt_pk_bf16_f32 v21, v50, v52
	v_lshl_add_u64 v[56:57], v[54:55], 0, v[56:57]
	global_store_dwordx4 v[56:57], v[18:21], off
	v_or_b32_e32 v17, s18, v27
	v_lshlrev_b32_e32 v22, 9, v17
	v_cvt_pk_bf16_f32 v18, v33, v23
	v_cvt_pk_bf16_f32 v19, v35, v39
	v_cvt_pk_bf16_f32 v20, v43, v49
	v_cvt_pk_bf16_f32 v21, v51, v53
	ds_read2_b32 v[32:33], v26 offset0:49 offset1:57
	ds_read2_b32 v[34:35], v26 offset0:16 offset1:24
	ds_read2_b32 v[38:39], v26 offset0:82 offset1:90
	ds_read2_b32 v[42:43], v26 offset0:115 offset1:123
	ds_read2_b32 v[48:49], v26 offset0:148 offset1:156
	ds_read2_b32 v[50:51], v26 offset0:181 offset1:189
	ds_read2_b32 v[52:53], v26 offset0:214 offset1:222
	ds_read2_b32 v[56:57], v26 offset0:247 offset1:255
	v_mov_b32_e32 v23, v36
	v_lshl_add_u64 v[22:23], v[54:55], 0, v[22:23]
	v_or_b32_e32 v17, s18, v28
	global_store_dwordx4 v[22:23], v[18:21], off
	v_lshlrev_b32_e32 v22, 9, v17
	v_mov_b32_e32 v23, v36
	s_waitcnt lgkmcnt(6)
	v_cvt_pk_bf16_f32 v18, v34, v32
	s_waitcnt lgkmcnt(4)
	v_cvt_pk_bf16_f32 v19, v38, v42
	s_waitcnt lgkmcnt(2)
	v_cvt_pk_bf16_f32 v20, v48, v50
	s_waitcnt lgkmcnt(0)
	v_cvt_pk_bf16_f32 v21, v52, v56
	v_lshl_add_u64 v[22:23], v[54:55], 0, v[22:23]
	v_or_b32_e32 v17, s18, v29
	global_store_dwordx4 v[22:23], v[18:21], off
	v_lshlrev_b32_e32 v22, 9, v17
	v_mov_b32_e32 v23, v36
	v_cvt_pk_bf16_f32 v18, v35, v33
	v_cvt_pk_bf16_f32 v19, v39, v43
	v_cvt_pk_bf16_f32 v20, v49, v51
	v_cvt_pk_bf16_f32 v21, v53, v57
	v_lshl_add_u64 v[22:23], v[54:55], 0, v[22:23]
	global_store_dwordx4 v[22:23], v[18:21], off

; __device__ __forceinline__ int srcmap(int mat, int p) {
;     ...
;     if (mat == MAT_UQ) { const int h = p / 96, w = p - h * 96; if (w < 64) return p; const int ww = w - 64; return h * 96 + 64 + (ww >> 1) + 16 * (ww & 1); }
; __device__ __forceinline__ void transpose_item(const float* __restrict__ W, int K, int N, bf16_t* WT, int KD, int item, int mat, const float* __restrict__ ks, float* scr, int lane) {
;     const int nkb = KD / 64, pb = item / nkb, kb = item - pb * nkb, p0 = pb * 32, k0 = kb * 64;
;     const int src = srcmap(mat, p0 + (lane & 31));
;     float tv[32];
; #pragma unroll
;     for (int i = 0; i < 32; ++i) {
;         const int k = k0 + 2 * i + (lane >> 5);
;         float v = 0.f;
;         if (src >= 0 && k < K) { v = W[(size_t)k * N + src]; if (ks) v *= ks[k]; }
;         tv[i] = v;
;     }
.LBB0_1985:
	s_andn2_b64 vcc, exec, s[0:1]
	s_cbranch_vccnz .LBB0_2085
	s_add_i32 s19, s27, 0xfffff480
	s_lshr_b32 s24, s19, 2
	s_lshl_b32 s18, s24, 5
	v_or_b32_e32 v20, s18, v1
	v_mul_u32_u24_e32 v17, 0xaaab, v20
	v_lshrrev_b32_e32 v17, 22, v17
	v_mul_lo_u16_e32 v17, 0x60, v17
	v_sub_u16_e32 v17, v20, v17
	v_cmp_lt_u16_e32 vcc, 63, v17
	s_and_saveexec_b64 s[0:1], vcc
	v_subrev_u32_e32 v18, 64, v17
	v_lshrrev_b32_e32 v18, 1, v18
	v_lshlrev_b32_e32 v19, 4, v17
	v_sub_u32_e32 v17, v20, v17
	v_and_b32_e32 v19, 16, v19
	v_add_u32_e32 v17, v17, v18
	v_add3_u32 v20, v17, v19, 64
	s_or_b64 exec, exec, s[0:1]
	s_load_dwordx2 s[0:1], s[6:7], 0x60
	s_load_dwordx2 s[34:35], s[6:7], 0x50
	v_readlane_b32 s30, v254, 27
	s_mul_i32 s25, s30, 0xc0000
	v_readlane_b32 s31, v254, 28
	s_waitcnt lgkmcnt(0)
	s_add_u32 s0, s0, s25
	s_mul_hi_i32 s25, s30, 0xc0000
	s_addc_u32 s1, s1, s25
	s_add_u32 s30, s34, s28
	s_addc_u32 s31, s35, s29
	s_lshl_b32 s24, s24, 8
	s_lshl_b32 s19, s19, 6
	s_sub_i32 s24, s19, s24
	v_mov_b32_e32 v21, v36
	s_cmp_lg_u64 s[34:35], 0
	v_cmp_lt_i32_e64 s[38:39], -1, v20
	v_or_b32_e32 v18, s24, v3
	v_lshl_add_u64 v[20:21], v[20:21], 2, s[0:1]
	s_cselect_b64 s[0:1], -1, 0
	v_cmp_gt_i32_e32 vcc, s96, v18
	v_cndmask_b32_e64 v19, 0, 1, s[0:1]
	s_and_b64 s[34:35], s[38:39], vcc
	v_mov_b32_e32 v17, 0
	v_cmp_ne_u32_e64 s[40:41], 1, v19
	v_mov_b32_e32 v22, 0
	v_mov_b32_e32 v136, 1.0
	v_mov_b32_e32 v137, 1.0
	v_mov_b32_e32 v138, 1.0
	v_mov_b32_e32 v139, 1.0
	v_mov_b32_e32 v140, 1.0
	v_mov_b32_e32 v141, 1.0
	v_mov_b32_e32 v142, 1.0
	v_mov_b32_e32 v143, 1.0
	v_mov_b32_e32 v144, 1.0
	v_mov_b32_e32 v145, 1.0
	v_mov_b32_e32 v146, 1.0
	v_mov_b32_e32 v147, 1.0
	v_mov_b32_e32 v148, 1.0
	v_mov_b32_e32 v149, 1.0
	v_mov_b32_e32 v150, 1.0
	v_mov_b32_e32 v151, 1.0
	v_mov_b32_e32 v152, 1.0
	v_mov_b32_e32 v153, 1.0
	v_mov_b32_e32 v154, 1.0
	v_mov_b32_e32 v155, 1.0
	v_mov_b32_e32 v156, 1.0
	v_mov_b32_e32 v157, 1.0
	v_mov_b32_e32 v158, 1.0
	v_mov_b32_e32 v159, 1.0
	v_mov_b32_e32 v174, 1.0
	v_mov_b32_e32 v175, 1.0
	v_mov_b32_e32 v176, 1.0
	v_mov_b32_e32 v177, 1.0
	v_mov_b32_e32 v178, 1.0
	v_mov_b32_e32 v179, 1.0
	v_mov_b32_e32 v180, 1.0
	v_mov_b32_e32 v181, 1.0
	s_and_saveexec_b64 s[0:1], s[34:35]
	s_cbranch_execz .LBB0_1991
	s_movk_i32 s19, 0xc00
	v_mad_i64_i32 v[22:23], s[34:35], v18, s19, v[20:21]
	global_load_dword v22, v[22:23], off
	s_and_b64 vcc, exec, s[40:41]
	s_cbranch_vccnz .LBB0_1991
	v_ashrrev_i32_e32 v19, 31, v18
	v_lshl_add_u64 v[32:33], v[18:19], 2, s[30:31]
	global_load_dword v136, v[32:33], off
.LBB0_1991:
	s_or_b64 exec, exec, s[0:1]
	v_or_b32_e32 v19, 2, v18
	v_cmp_gt_i32_e32 vcc, s96, v19
	s_and_b64 s[34:35], s[38:39], vcc
	s_and_saveexec_b64 s[0:1], s[34:35]
	s_cbranch_execz .LBB0_1994
	s_movk_i32 s19, 0xc00
	v_mad_i64_i32 v[32:33], s[34:35], v19, s19, v[20:21]
	global_load_dword v17, v[32:33], off
	s_and_b64 vcc, exec, s[40:41]
	s_cbranch_vccnz .LBB0_1994
	v_ashrrev_i32_e32 v19, 31, v18
	v_lshl_add_u64 v[32:33], v[18:19], 2, s[30:31]
	global_load_dword v137, v[32:33], off offset:8
.LBB0_1994:
	s_or_b64 exec, exec, s[0:1]
	v_or_b32_e32 v19, 4, v18
	v_cmp_gt_i32_e32 vcc, s96, v19
	s_and_b64 s[34:35], s[38:39], vcc
	v_mov_b32_e32 v23, 0
	v_mov_b32_e32 v32, 0
	s_and_saveexec_b64 s[0:1], s[34:35]
	s_cbranch_execz .LBB0_1997
	s_movk_i32 s19, 0xc00
	v_mad_i64_i32 v[32:33], s[34:35], v19, s19, v[20:21]
	global_load_dword v32, v[32:33], off
	s_and_b64 vcc, exec, s[40:41]
	s_cbranch_vccnz .LBB0_1997
	v_ashrrev_i32_e32 v19, 31, v18
	v_lshl_add_u64 v[34:35], v[18:19], 2, s[30:31]
	global_load_dword v138, v[34:35], off offset:16
.LBB0_1997:
	s_or_b64 exec, exec, s[0:1]
	v_or_b32_e32 v19, 6, v18
	v_cmp_gt_i32_e32 vcc, s96, v19
	s_and_b64 s[34:35], s[38:39], vcc
	s_and_saveexec_b64 s[0:1], s[34:35]
	s_cbranch_execz .LBB0_2000
	s_movk_i32 s19, 0xc00
	v_mad_i64_i32 v[34:35], s[34:35], v19, s19, v[20:21]
	global_load_dword v23, v[34:35], off
	s_and_b64 vcc, exec, s[40:41]
	s_cbranch_vccnz .LBB0_2000
	v_ashrrev_i32_e32 v19, 31, v18
	v_lshl_add_u64 v[34:35], v[18:19], 2, s[30:31]
	global_load_dword v139, v[34:35], off offset:24
.LBB0_2000:
	s_or_b64 exec, exec, s[0:1]
	v_or_b32_e32 v19, 8, v18
	v_cmp_gt_i32_e32 vcc, s96, v19
	s_and_b64 s[34:35], s[38:39], vcc
	v_mov_b32_e32 v33, 0
	v_mov_b32_e32 v34, 0
	s_and_saveexec_b64 s[0:1], s[34:35]
	s_cbranch_execz .LBB0_2003
	s_movk_i32 s19, 0xc00
	v_mad_i64_i32 v[34:35], s[34:35], v19, s19, v[20:21]
	global_load_dword v34, v[34:35], off
	s_and_b64 vcc, exec, s[40:41]
	s_cbranch_vccnz .LBB0_2003
	v_ashrrev_i32_e32 v19, 31, v18
	v_lshl_add_u64 v[38:39], v[18:19], 2, s[30:31]
	global_load_dword v140, v[38:39], off offset:32
.LBB0_2003:
	s_or_b64 exec, exec, s[0:1]
	v_or_b32_e32 v19, 10, v18
	v_cmp_gt_i32_e32 vcc, s96, v19
	s_and_b64 s[34:35], s[38:39], vcc
	s_and_saveexec_b64 s[0:1], s[34:35]
	s_cbranch_execz .LBB0_2006
	s_movk_i32 s19, 0xc00
	v_mad_i64_i32 v[38:39], s[34:35], v19, s19, v[20:21]
	global_load_dword v33, v[38:39], off
	s_and_b64 vcc, exec, s[40:41]
	s_cbranch_vccnz .LBB0_2006
	v_ashrrev_i32_e32 v19, 31, v18
	v_lshl_add_u64 v[38:39], v[18:19], 2, s[30:31]
	global_load_dword v141, v[38:39], off offset:40
.LBB0_2006:
	s_or_b64 exec, exec, s[0:1]
	v_or_b32_e32 v19, 12, v18
	v_cmp_gt_i32_e32 vcc, s96, v19
	s_and_b64 s[34:35], s[38:39], vcc
	v_mov_b32_e32 v35, 0
	v_mov_b32_e32 v37, 0
	s_and_saveexec_b64 s[0:1], s[34:35]
	s_cbranch_execz .LBB0_2009
	s_movk_i32 s19, 0xc00
	v_mad_i64_i32 v[38:39], s[34:35], v19, s19, v[20:21]
	global_load_dword v37, v[38:39], off
	s_and_b64 vcc, exec, s[40:41]
	s_cbranch_vccnz .LBB0_2009
	v_ashrrev_i32_e32 v19, 31, v18
	v_lshl_add_u64 v[38:39], v[18:19], 2, s[30:31]
	global_load_dword v142, v[38:39], off offset:48
; __device__ __forceinline__ void transpose_item(const float* __restrict__ W, int K, int N, bf16_t* WT, int KD, int item, int mat, const float* __restrict__ ks, float* scr, int lane) {
;     ...
;     for (int i = 0; i < 32; ++i) {
;         const int k = k0 + 2 * i + (lane >> 5);
;         float v = 0.f;
;         if (src >= 0 && k < K) { v = W[(size_t)k * N + src]; if (ks) v *= ks[k]; }
;         tv[i] = v;
;     }
.LBB0_2009:
	s_or_b64 exec, exec, s[0:1]
	v_or_b32_e32 v19, 14, v18
	v_cmp_gt_i32_e32 vcc, s96, v19
	s_and_b64 s[34:35], s[38:39], vcc
	s_and_saveexec_b64 s[0:1], s[34:35]
	s_cbranch_execz .LBB0_2012
	s_movk_i32 s19, 0xc00
	v_mad_i64_i32 v[38:39], s[34:35], v19, s19, v[20:21]
	global_load_dword v35, v[38:39], off
	s_and_b64 vcc, exec, s[40:41]
	s_cbranch_vccnz .LBB0_2012
	v_ashrrev_i32_e32 v19, 31, v18
	v_lshl_add_u64 v[38:39], v[18:19], 2, s[30:31]
	global_load_dword v143, v[38:39], off offset:56
.LBB0_2012:
	s_or_b64 exec, exec, s[0:1]
	v_or_b32_e32 v19, 16, v18
	v_cmp_gt_i32_e32 vcc, s96, v19
	s_and_b64 s[34:35], s[38:39], vcc
	v_mov_b32_e32 v38, 0
	v_mov_b32_e32 v39, 0
	s_and_saveexec_b64 s[0:1], s[34:35]
	s_cbranch_execz .LBB0_2015
	s_movk_i32 s19, 0xc00
	v_mad_i64_i32 v[42:43], s[34:35], v19, s19, v[20:21]
	global_load_dword v39, v[42:43], off
	s_and_b64 vcc, exec, s[40:41]
	s_cbranch_vccnz .LBB0_2015
	v_ashrrev_i32_e32 v19, 31, v18
	v_lshl_add_u64 v[42:43], v[18:19], 2, s[30:31]
	global_load_dword v144, v[42:43], off offset:64
.LBB0_2015:
	s_or_b64 exec, exec, s[0:1]
	v_or_b32_e32 v19, 18, v18
	v_cmp_gt_i32_e32 vcc, s96, v19
	s_and_b64 s[34:35], s[38:39], vcc
	s_and_saveexec_b64 s[0:1], s[34:35]
	s_cbranch_execz .LBB0_2018
	s_movk_i32 s19, 0xc00
	v_mad_i64_i32 v[42:43], s[34:35], v19, s19, v[20:21]
	global_load_dword v38, v[42:43], off
	s_and_b64 vcc, exec, s[40:41]
	s_cbranch_vccnz .LBB0_2018
	v_ashrrev_i32_e32 v19, 31, v18
	v_lshl_add_u64 v[42:43], v[18:19], 2, s[30:31]
	global_load_dword v145, v[42:43], off offset:72
.LBB0_2018:
	s_or_b64 exec, exec, s[0:1]
	v_or_b32_e32 v19, 20, v18
	v_cmp_gt_i32_e32 vcc, s96, v19
	s_and_b64 s[34:35], s[38:39], vcc
	v_mov_b32_e32 v41, 0
	v_mov_b32_e32 v42, 0
	s_and_saveexec_b64 s[0:1], s[34:35]
	s_cbranch_execz .LBB0_2021
	s_movk_i32 s19, 0xc00
	v_mad_i64_i32 v[42:43], s[34:35], v19, s19, v[20:21]
	global_load_dword v42, v[42:43], off
	s_and_b64 vcc, exec, s[40:41]
	s_cbranch_vccnz .LBB0_2021
	v_ashrrev_i32_e32 v19, 31, v18
	v_lshl_add_u64 v[48:49], v[18:19], 2, s[30:31]
	global_load_dword v146, v[48:49], off offset:80
.LBB0_2021:
	s_or_b64 exec, exec, s[0:1]
	v_or_b32_e32 v19, 22, v18
	v_cmp_gt_i32_e32 vcc, s96, v19
	s_and_b64 s[34:35], s[38:39], vcc
	s_and_saveexec_b64 s[0:1], s[34:35]
	s_cbranch_execz .LBB0_2024
	s_movk_i32 s19, 0xc00
	v_mad_i64_i32 v[48:49], s[34:35], v19, s19, v[20:21]
	global_load_dword v41, v[48:49], off
	s_and_b64 vcc, exec, s[40:41]
	s_cbranch_vccnz .LBB0_2024
	v_ashrrev_i32_e32 v19, 31, v18
	v_lshl_add_u64 v[48:49], v[18:19], 2, s[30:31]
	global_load_dword v147, v[48:49], off offset:88
.LBB0_2024:
	s_or_b64 exec, exec, s[0:1]
	v_or_b32_e32 v19, 24, v18
	v_cmp_gt_i32_e32 vcc, s96, v19
	s_and_b64 s[34:35], s[38:39], vcc
	v_mov_b32_e32 v43, 0
	v_mov_b32_e32 v48, 0
	s_and_saveexec_b64 s[0:1], s[34:35]
	s_cbranch_execz .LBB0_2027
	s_movk_i32 s19, 0xc00
	v_mad_i64_i32 v[48:49], s[34:35], v19, s19, v[20:21]
	global_load_dword v48, v[48:49], off
	s_and_b64 vcc, exec, s[40:41]
	s_cbranch_vccnz .LBB0_2027
	v_ashrrev_i32_e32 v19, 31, v18
	v_lshl_add_u64 v[50:51], v[18:19], 2, s[30:31]
	global_load_dword v148, v[50:51], off offset:96
.LBB0_2027:
	s_or_b64 exec, exec, s[0:1]
	v_or_b32_e32 v19, 26, v18
	v_cmp_gt_i32_e32 vcc, s96, v19
	s_and_b64 s[34:35], s[38:39], vcc
	s_and_saveexec_b64 s[0:1], s[34:35]
	s_cbranch_execz .LBB0_2030
	s_movk_i32 s19, 0xc00
	v_mad_i64_i32 v[50:51], s[34:35], v19, s19, v[20:21]
	global_load_dword v43, v[50:51], off
	s_and_b64 vcc, exec, s[40:41]
	s_cbranch_vccnz .LBB0_2030
	v_ashrrev_i32_e32 v19, 31, v18
	v_lshl_add_u64 v[50:51], v[18:19], 2, s[30:31]
	global_load_dword v149, v[50:51], off offset:104
.LBB0_2030:
	s_or_b64 exec, exec, s[0:1]
	v_or_b32_e32 v19, 28, v18
	v_cmp_gt_i32_e32 vcc, s96, v19
	s_and_b64 s[34:35], s[38:39], vcc
	v_mov_b32_e32 v49, 0
	v_mov_b32_e32 v50, 0
	s_and_saveexec_b64 s[0:1], s[34:35]
	s_cbranch_execz .LBB0_2033
	s_movk_i32 s19, 0xc00
	v_mad_i64_i32 v[50:51], s[34:35], v19, s19, v[20:21]
	global_load_dword v50, v[50:51], off
	s_and_b64 vcc, exec, s[40:41]
	s_cbranch_vccnz .LBB0_2033
	v_ashrrev_i32_e32 v19, 31, v18
	v_lshl_add_u64 v[52:53], v[18:19], 2, s[30:31]
	global_load_dword v150, v[52:53], off offset:112
.LBB0_2033:
	s_or_b64 exec, exec, s[0:1]
	v_or_b32_e32 v19, 30, v18
	v_cmp_gt_i32_e32 vcc, s96, v19
	s_and_b64 s[34:35], s[38:39], vcc
	s_and_saveexec_b64 s[0:1], s[34:35]
	s_cbranch_execz .LBB0_2036
	s_movk_i32 s19, 0xc00
	v_mad_i64_i32 v[52:53], s[34:35], v19, s19, v[20:21]
	global_load_dword v49, v[52:53], off
	s_and_b64 vcc, exec, s[40:41]
	s_cbranch_vccnz .LBB0_2036
	v_ashrrev_i32_e32 v19, 31, v18
	v_lshl_add_u64 v[52:53], v[18:19], 2, s[30:31]
	global_load_dword v151, v[52:53], off offset:120
.LBB0_2036:
	s_or_b64 exec, exec, s[0:1]
	v_or_b32_e32 v19, 32, v18
	v_cmp_gt_i32_e32 vcc, s96, v19
	s_and_b64 s[34:35], s[38:39], vcc
	v_mov_b32_e32 v51, 0
	v_mov_b32_e32 v52, 0
	s_and_saveexec_b64 s[0:1], s[34:35]
	s_cbranch_execz .LBB0_2039
	s_movk_i32 s19, 0xc00
	v_mad_i64_i32 v[52:53], s[34:35], v19, s19, v[20:21]
	global_load_dword v52, v[52:53], off
	s_and_b64 vcc, exec, s[40:41]
	s_cbranch_vccnz .LBB0_2039
	v_ashrrev_i32_e32 v19, 31, v18
	v_lshl_add_u64 v[54:55], v[18:19], 2, s[30:31]
	global_load_dword v152, v[54:55], off offset:128
.LBB0_2039:
	s_or_b64 exec, exec, s[0:1]
	v_or_b32_e32 v19, 34, v18
	v_cmp_gt_i32_e32 vcc, s96, v19
	s_and_b64 s[34:35], s[38:39], vcc
	s_and_saveexec_b64 s[0:1], s[34:35]
	s_cbranch_execz .LBB0_2042
	s_movk_i32 s19, 0xc00
	v_mad_i64_i32 v[54:55], s[34:35], v19, s19, v[20:21]
	global_load_dword v51, v[54:55], off
	s_and_b64 vcc, exec, s[40:41]
	s_cbranch_vccnz .LBB0_2042
	v_ashrrev_i32_e32 v19, 31, v18
	v_lshl_add_u64 v[54:55], v[18:19], 2, s[30:31]
	global_load_dword v153, v[54:55], off offset:136
; __device__ __forceinline__ void transpose_item(const float* __restrict__ W, int K, int N, bf16_t* WT, int KD, int item, int mat, const float* __restrict__ ks, float* scr, int lane) {
;     ...
;     for (int i = 0; i < 32; ++i) {
;         const int k = k0 + 2 * i + (lane >> 5);
;         float v = 0.f;
;         if (src >= 0 && k < K) { v = W[(size_t)k * N + src]; if (ks) v *= ks[k]; }
;         tv[i] = v;
;     }
.LBB0_2042:
	s_or_b64 exec, exec, s[0:1]
	v_or_b32_e32 v19, 36, v18
	v_cmp_gt_i32_e32 vcc, s96, v19
	s_and_b64 s[34:35], s[38:39], vcc
	v_mov_b32_e32 v53, 0
	v_mov_b32_e32 v54, 0
	s_and_saveexec_b64 s[0:1], s[34:35]
	s_cbranch_execz .LBB0_2045
	s_movk_i32 s19, 0xc00
	v_mad_i64_i32 v[54:55], s[34:35], v19, s19, v[20:21]
	global_load_dword v54, v[54:55], off
	s_and_b64 vcc, exec, s[40:41]
	s_cbranch_vccnz .LBB0_2045
	v_ashrrev_i32_e32 v19, 31, v18
	v_lshl_add_u64 v[56:57], v[18:19], 2, s[30:31]
	global_load_dword v154, v[56:57], off offset:144
.LBB0_2045:
	s_or_b64 exec, exec, s[0:1]
	v_or_b32_e32 v19, 38, v18
	v_cmp_gt_i32_e32 vcc, s96, v19
	s_and_b64 s[34:35], s[38:39], vcc
	s_and_saveexec_b64 s[0:1], s[34:35]
	s_cbranch_execz .LBB0_2048
	s_movk_i32 s19, 0xc00
	v_mad_i64_i32 v[56:57], s[34:35], v19, s19, v[20:21]
	global_load_dword v53, v[56:57], off
	s_and_b64 vcc, exec, s[40:41]
	s_cbranch_vccnz .LBB0_2048
	v_ashrrev_i32_e32 v19, 31, v18
	v_lshl_add_u64 v[56:57], v[18:19], 2, s[30:31]
	global_load_dword v155, v[56:57], off offset:152
.LBB0_2048:
	s_or_b64 exec, exec, s[0:1]
	v_or_b32_e32 v19, 40, v18
	v_cmp_gt_i32_e32 vcc, s96, v19
	s_and_b64 s[34:35], s[38:39], vcc
	v_mov_b32_e32 v55, 0
	v_mov_b32_e32 v56, 0
	s_and_saveexec_b64 s[0:1], s[34:35]
	s_cbranch_execz .LBB0_2051
	s_movk_i32 s19, 0xc00
	v_mad_i64_i32 v[56:57], s[34:35], v19, s19, v[20:21]
	global_load_dword v56, v[56:57], off
	s_and_b64 vcc, exec, s[40:41]
	s_cbranch_vccnz .LBB0_2051
	v_ashrrev_i32_e32 v19, 31, v18
	v_lshl_add_u64 v[58:59], v[18:19], 2, s[30:31]
	global_load_dword v156, v[58:59], off offset:160
.LBB0_2051:
	s_or_b64 exec, exec, s[0:1]
	v_or_b32_e32 v19, 42, v18
	v_cmp_gt_i32_e32 vcc, s96, v19
	s_and_b64 s[34:35], s[38:39], vcc
	s_and_saveexec_b64 s[0:1], s[34:35]
	s_cbranch_execz .LBB0_2054
	s_movk_i32 s19, 0xc00
	v_mad_i64_i32 v[58:59], s[34:35], v19, s19, v[20:21]
	global_load_dword v55, v[58:59], off
	s_and_b64 vcc, exec, s[40:41]
	s_cbranch_vccnz .LBB0_2054
	v_ashrrev_i32_e32 v19, 31, v18
	v_lshl_add_u64 v[58:59], v[18:19], 2, s[30:31]
	global_load_dword v157, v[58:59], off offset:168
.LBB0_2054:
	s_or_b64 exec, exec, s[0:1]
	v_or_b32_e32 v19, 44, v18
	v_cmp_gt_i32_e32 vcc, s96, v19
	s_and_b64 s[34:35], s[38:39], vcc
	v_mov_b32_e32 v57, 0
	v_mov_b32_e32 v58, 0
	s_and_saveexec_b64 s[0:1], s[34:35]
	s_cbranch_execz .LBB0_2057
	s_movk_i32 s19, 0xc00
	v_mad_i64_i32 v[58:59], s[34:35], v19, s19, v[20:21]
	global_load_dword v58, v[58:59], off
	s_and_b64 vcc, exec, s[40:41]
	s_cbranch_vccnz .LBB0_2057
	v_ashrrev_i32_e32 v19, 31, v18
	v_lshl_add_u64 v[60:61], v[18:19], 2, s[30:31]
	global_load_dword v158, v[60:61], off offset:176
.LBB0_2057:
	s_or_b64 exec, exec, s[0:1]
	v_or_b32_e32 v19, 46, v18
	v_cmp_gt_i32_e32 vcc, s96, v19
	s_and_b64 s[34:35], s[38:39], vcc
	s_and_saveexec_b64 s[0:1], s[34:35]
	s_cbranch_execz .LBB0_2060
	s_movk_i32 s19, 0xc00
	v_mad_i64_i32 v[60:61], s[34:35], v19, s19, v[20:21]
	global_load_dword v57, v[60:61], off
	s_and_b64 vcc, exec, s[40:41]
	s_cbranch_vccnz .LBB0_2060
	v_ashrrev_i32_e32 v19, 31, v18
	v_lshl_add_u64 v[60:61], v[18:19], 2, s[30:31]
	global_load_dword v159, v[60:61], off offset:184
.LBB0_2060:
	s_or_b64 exec, exec, s[0:1]
	v_or_b32_e32 v19, 48, v18
	v_cmp_gt_i32_e32 vcc, s96, v19
	s_and_b64 s[34:35], s[38:39], vcc
	v_mov_b32_e32 v59, 0
	v_mov_b32_e32 v60, 0
	s_and_saveexec_b64 s[0:1], s[34:35]
	s_cbranch_execz .LBB0_2063
	s_movk_i32 s19, 0xc00
	v_mad_i64_i32 v[60:61], s[34:35], v19, s19, v[20:21]
	global_load_dword v60, v[60:61], off
	s_and_b64 vcc, exec, s[40:41]
	s_cbranch_vccnz .LBB0_2063
	v_ashrrev_i32_e32 v19, 31, v18
	v_lshl_add_u64 v[62:63], v[18:19], 2, s[30:31]
	global_load_dword v174, v[62:63], off offset:192
.LBB0_2063:
	s_or_b64 exec, exec, s[0:1]
	v_or_b32_e32 v19, 50, v18
	v_cmp_gt_i32_e32 vcc, s96, v19
	s_and_b64 s[34:35], s[38:39], vcc
	s_and_saveexec_b64 s[0:1], s[34:35]
	s_cbranch_execz .LBB0_2066
	s_movk_i32 s19, 0xc00
	v_mad_i64_i32 v[62:63], s[34:35], v19, s19, v[20:21]
	global_load_dword v59, v[62:63], off
	s_and_b64 vcc, exec, s[40:41]
	s_cbranch_vccnz .LBB0_2066
	v_ashrrev_i32_e32 v19, 31, v18
	v_lshl_add_u64 v[62:63], v[18:19], 2, s[30:31]
	global_load_dword v175, v[62:63], off offset:200
.LBB0_2066:
	s_or_b64 exec, exec, s[0:1]
	v_or_b32_e32 v19, 52, v18
	v_cmp_gt_i32_e32 vcc, s96, v19
	s_and_b64 s[34:35], s[38:39], vcc
	v_mov_b32_e32 v61, 0
	v_mov_b32_e32 v62, 0
	s_and_saveexec_b64 s[0:1], s[34:35]
	s_cbranch_execz .LBB0_2069
	s_movk_i32 s19, 0xc00
	v_mad_i64_i32 v[62:63], s[34:35], v19, s19, v[20:21]
	global_load_dword v62, v[62:63], off
	s_and_b64 vcc, exec, s[40:41]
	s_cbranch_vccnz .LBB0_2069
	v_ashrrev_i32_e32 v19, 31, v18
	v_lshl_add_u64 v[64:65], v[18:19], 2, s[30:31]
	global_load_dword v176, v[64:65], off offset:208
.LBB0_2069:
	s_or_b64 exec, exec, s[0:1]
	v_or_b32_e32 v19, 54, v18
	v_cmp_gt_i32_e32 vcc, s96, v19
	s_and_b64 s[34:35], s[38:39], vcc
	s_and_saveexec_b64 s[0:1], s[34:35]
	s_cbranch_execz .LBB0_2072
	s_movk_i32 s19, 0xc00
	v_mad_i64_i32 v[64:65], s[34:35], v19, s19, v[20:21]
	global_load_dword v61, v[64:65], off
	s_and_b64 vcc, exec, s[40:41]
	s_cbranch_vccnz .LBB0_2072
	v_ashrrev_i32_e32 v19, 31, v18
	v_lshl_add_u64 v[64:65], v[18:19], 2, s[30:31]
	global_load_dword v177, v[64:65], off offset:216
.LBB0_2072:
	s_or_b64 exec, exec, s[0:1]
	v_or_b32_e32 v19, 56, v18
	v_cmp_gt_i32_e32 vcc, s96, v19
	s_and_b64 s[34:35], s[38:39], vcc
	v_mov_b32_e32 v63, 0
	v_mov_b32_e32 v64, 0
	s_and_saveexec_b64 s[0:1], s[34:35]
	s_cbranch_execz .LBB0_2075
	s_movk_i32 s19, 0xc00
	v_mad_i64_i32 v[64:65], s[34:35], v19, s19, v[20:21]
	global_load_dword v64, v[64:65], off
	s_and_b64 vcc, exec, s[40:41]
	s_cbranch_vccnz .LBB0_2075
	v_ashrrev_i32_e32 v19, 31, v18
	v_lshl_add_u64 v[66:67], v[18:19], 2, s[30:31]
	global_load_dword v178, v[66:67], off offset:224
; __device__ __forceinline__ unsigned pk2(float lo, float hi) { f32x2_t v = {lo, hi}; bf16x2_t b = __builtin_convertvector(v, bf16x2_t); return __builtin_bit_cast(unsigned, b); }
; __device__ __forceinline__ void transpose_item(const float* __restrict__ W, int K, int N, bf16_t* WT, int KD, int item, int mat, const float* __restrict__ ks, float* scr, int lane) {
;     ...
;     for (int i = 0; i < 32; ++i) {
;         const int k = k0 + 2 * i + (lane >> 5);
;         float v = 0.f;
;         if (src >= 0 && k < K) { v = W[(size_t)k * N + src]; if (ks) v *= ks[k]; }
;         tv[i] = v;
;     }
; #pragma unroll
;     for (int i = 0; i < 32; ++i) scr[(2 * i + (lane >> 5)) * 33 + (lane & 31)] = tv[i];
;     __builtin_amdgcn_fence(__ATOMIC_RELEASE, "workgroup"); __builtin_amdgcn_wave_barrier();
;     const int c = lane & 7;
; #pragma unroll
;     for (int j = 0; j < 4; ++j) {
;         const int n = (lane >> 3) + 8 * j; const float* s = scr + (8 * c) * 33 + n;
;         u32x4 o; o.x = pk2(s[0 * 33], s[1 * 33]); o.y = pk2(s[2 * 33], s[3 * 33]); o.z = pk2(s[4 * 33], s[5 * 33]); o.w = pk2(s[6 * 33], s[7 * 33]);
;         *(u32x4*)(WT + (size_t)(p0 + n) * KD + k0 + 8 * c) = o;
.LBB0_2075:
	s_or_b64 exec, exec, s[0:1]
	v_or_b32_e32 v19, 58, v18
	v_cmp_gt_i32_e32 vcc, s96, v19
	s_and_b64 s[34:35], s[38:39], vcc
	s_and_saveexec_b64 s[0:1], s[34:35]
	s_cbranch_execz .LBB0_2078
	s_movk_i32 s19, 0xc00
	v_mad_i64_i32 v[66:67], s[34:35], v19, s19, v[20:21]
	global_load_dword v63, v[66:67], off
	s_and_b64 vcc, exec, s[40:41]
	s_cbranch_vccnz .LBB0_2078
	v_ashrrev_i32_e32 v19, 31, v18
	v_lshl_add_u64 v[66:67], v[18:19], 2, s[30:31]
	global_load_dword v179, v[66:67], off offset:232
.LBB0_2078:
	s_or_b64 exec, exec, s[0:1]
	v_or_b32_e32 v19, 60, v18
	v_cmp_gt_i32_e32 vcc, s96, v19
	s_and_b64 s[34:35], s[38:39], vcc
	v_mov_b32_e32 v65, 0
	v_mov_b32_e32 v66, 0
	s_and_saveexec_b64 s[0:1], s[34:35]
	s_cbranch_execz .LBB0_2081
	s_movk_i32 s19, 0xc00
	v_mad_i64_i32 v[66:67], s[34:35], v19, s19, v[20:21]
	global_load_dword v66, v[66:67], off
	s_and_b64 vcc, exec, s[40:41]
	s_cbranch_vccnz .LBB0_2081
	v_ashrrev_i32_e32 v19, 31, v18
	s_waitcnt vmcnt(0)
	v_lshl_add_u64 v[68:69], v[18:19], 2, s[30:31]
	global_load_dword v180, v[68:69], off offset:240
.LBB0_2081:
	s_or_b64 exec, exec, s[0:1]
	v_or_b32_e32 v19, 62, v18
	v_cmp_gt_i32_e32 vcc, s96, v19
	s_and_b64 s[34:35], s[38:39], vcc
	s_and_saveexec_b64 s[0:1], s[34:35]
	s_cbranch_execz .LBB0_2084
	s_movk_i32 s19, 0xc00
	v_mad_i64_i32 v[20:21], s[34:35], v19, s19, v[20:21]
	global_load_dword v65, v[20:21], off
	s_and_b64 vcc, exec, s[40:41]
	s_cbranch_vccnz .LBB0_2084
	v_ashrrev_i32_e32 v19, 31, v18
	v_lshl_add_u64 v[18:19], v[18:19], 2, s[30:31]
	global_load_dword v181, v[18:19], off offset:248
.LBB0_2084:
	s_or_b64 exec, exec, s[0:1]
	s_waitcnt vmcnt(0)
	v_mul_f32_e32 v22, v22, v136
	v_mul_f32_e32 v17, v17, v137
	v_mul_f32_e32 v32, v32, v138
	v_mul_f32_e32 v23, v23, v139
	v_mul_f32_e32 v34, v34, v140
	v_mul_f32_e32 v33, v33, v141
	v_mul_f32_e32 v37, v37, v142
	v_mul_f32_e32 v35, v35, v143
	v_mul_f32_e32 v39, v39, v144
	v_mul_f32_e32 v38, v38, v145
	v_mul_f32_e32 v42, v42, v146
	v_mul_f32_e32 v41, v41, v147
	v_mul_f32_e32 v48, v48, v148
	v_mul_f32_e32 v43, v43, v149
	v_mul_f32_e32 v50, v50, v150
	v_mul_f32_e32 v49, v49, v151
	v_mul_f32_e32 v52, v52, v152
	v_mul_f32_e32 v51, v51, v153
	v_mul_f32_e32 v54, v54, v154
	v_mul_f32_e32 v53, v53, v155
	v_mul_f32_e32 v56, v56, v156
	v_mul_f32_e32 v55, v55, v157
	v_mul_f32_e32 v58, v58, v158
	v_mul_f32_e32 v57, v57, v159
	v_mul_f32_e32 v60, v60, v174
	v_mul_f32_e32 v59, v59, v175
	v_mul_f32_e32 v62, v62, v176
	v_mul_f32_e32 v61, v61, v177
	v_mul_f32_e32 v64, v64, v178
	v_mul_f32_e32 v63, v63, v179
	v_mul_f32_e32 v66, v66, v180
	v_mul_f32_e32 v65, v65, v181
	s_waitcnt vmcnt(0)
	ds_write2_b32 v24, v22, v17 offset1:66
	ds_write2_b32 v24, v32, v23 offset0:132 offset1:198
	v_add_u32_e32 v17, 0x400, v24
	ds_write2_b32 v17, v34, v33 offset0:8 offset1:74
	ds_write2_b32 v17, v37, v35 offset0:140 offset1:206
	v_add_u32_e32 v17, 0x800, v24
	ds_write2_b32 v17, v39, v38 offset0:16 offset1:82
	ds_write2_b32 v17, v42, v41 offset0:148 offset1:214
	v_add_u32_e32 v17, 0xc00, v24
	ds_write2_b32 v17, v48, v43 offset0:24 offset1:90
	ds_write2_b32 v17, v50, v49 offset0:156 offset1:222
	v_add_u32_e32 v17, 0x1000, v24
	ds_write2_b32 v17, v52, v51 offset0:32 offset1:98
	ds_write2_b32 v17, v54, v53 offset0:164 offset1:230
	v_add_u32_e32 v17, 0x1400, v24
	ds_write2_b32 v17, v56, v55 offset0:40 offset1:106
	ds_write2_b32 v17, v58, v57 offset0:172 offset1:238
	v_add_u32_e32 v17, 0x1800, v24
	ds_write2_b32 v17, v60, v59 offset0:48 offset1:114
	ds_write2_b32 v17, v62, v61 offset0:180 offset1:246
	v_add_u32_e32 v17, 0x1c00, v24
	ds_write2_b32 v17, v64, v63 offset0:56 offset1:122
	ds_write2_b32 v17, v66, v65 offset0:188 offset1:254
	s_waitcnt lgkmcnt(0)
	ds_read2_b32 v[22:23], v26 offset0:33 offset1:41
	ds_read2_b32 v[32:33], v26 offset1:8
	ds_read2_b32 v[34:35], v26 offset0:66 offset1:74
	ds_read2_b32 v[38:39], v26 offset0:99 offset1:107
	ds_read2_b32 v[42:43], v26 offset0:132 offset1:140
	ds_read2_b32 v[48:49], v26 offset0:165 offset1:173
	ds_read2_b32 v[50:51], v26 offset0:198 offset1:206
	ds_read2_b32 v[52:53], v26 offset0:231 offset1:239
	s_ashr_i32 s25, s24, 31
	v_or_b32_e32 v17, s18, v25
	v_lshl_add_u64 v[54:55], s[24:25], 1, v[12:13]
	v_lshlrev_b32_e32 v56, 9, v17
	v_mov_b32_e32 v57, v36
	s_waitcnt lgkmcnt(6)
	v_cvt_pk_bf16_f32 v18, v32, v22
	s_waitcnt lgkmcnt(4)
	v_cvt_pk_bf16_f32 v19, v34, v38
	s_waitcnt lgkmcnt(2)
	v_cvt_pk_bf16_f32 v20, v42, v48
	s_waitcnt lgkmcnt(0)
	v_cvt_pk_bf16_f32 v21, v50, v52
	v_lshl_add_u64 v[56:57], v[54:55], 0, v[56:57]
	global_store_dwordx4 v[56:57], v[18:21], off
	v_or_b32_e32 v17, s18, v27
	v_lshlrev_b32_e32 v22, 9, v17
	v_cvt_pk_bf16_f32 v18, v33, v23
	v_cvt_pk_bf16_f32 v19, v35, v39
	v_cvt_pk_bf16_f32 v20, v43, v49
	v_cvt_pk_bf16_f32 v21, v51, v53
	ds_read2_b32 v[32:33], v26 offset0:49 offset1:57
	ds_read2_b32 v[34:35], v26 offset0:16 offset1:24
	ds_read2_b32 v[38:39], v26 offset0:82 offset1:90
	ds_read2_b32 v[42:43], v26 offset0:115 offset1:123
	ds_read2_b32 v[48:49], v26 offset0:148 offset1:156
	ds_read2_b32 v[50:51], v26 offset0:181 offset1:189
	ds_read2_b32 v[52:53], v26 offset0:214 offset1:222
	ds_read2_b32 v[56:57], v26 offset0:247 offset1:255
	v_mov_b32_e32 v23, v36
	v_lshl_add_u64 v[22:23], v[54:55], 0, v[22:23]
	v_or_b32_e32 v17, s18, v28
	global_store_dwordx4 v[22:23], v[18:21], off
	v_lshlrev_b32_e32 v22, 9, v17
	v_mov_b32_e32 v23, v36
	s_waitcnt lgkmcnt(6)
	v_cvt_pk_bf16_f32 v18, v34, v32
	s_waitcnt lgkmcnt(4)
	v_cvt_pk_bf16_f32 v19, v38, v42
	s_waitcnt lgkmcnt(2)
	v_cvt_pk_bf16_f32 v20, v48, v50
	s_waitcnt lgkmcnt(0)
	v_cvt_pk_bf16_f32 v21, v52, v56
	v_lshl_add_u64 v[22:23], v[54:55], 0, v[22:23]
	v_or_b32_e32 v17, s18, v29
	global_store_dwordx4 v[22:23], v[18:21], off
	v_lshlrev_b32_e32 v22, 9, v17
	v_mov_b32_e32 v23, v36
	v_cvt_pk_bf16_f32 v18, v35, v33
	v_cvt_pk_bf16_f32 v19, v39, v43
	v_cvt_pk_bf16_f32 v20, v49, v51
	v_cvt_pk_bf16_f32 v21, v53, v57
	v_lshl_add_u64 v[22:23], v[54:55], 0, v[22:23]
	global_store_dwordx4 v[22:23], v[18:21], off
